# scan pass 2: chunk-carry tables touched once (32 entries ahead) before the composition loop so its trips hit cache
# baseline (speedup 1.0000x reference)
.LBB0_1517:
	s_or_b64 exec, exec, s[2:3]
	v_sub_u32_e32 v32, v28, v30
	v_cmp_gt_u32_e32 vcc, -3, v32
	s_and_saveexec_b64 s[10:11], vcc
	s_cbranch_execz .LBB0_1521
	v_add3_u32 v28, v28, s17, v29
	v_ashrrev_i32_e32 v29, 31, v28
	v_lshlrev_b64 v[28:29], 12, v[28:29]
	v_lshl_add_u64 v[28:29], v[20:21], 0, v[28:29]
	s_mov_b64 s[12:13], 0
	s_mov_b64 vcc, 0x1000
	s_mov_b32 s2, 0xffeffff0
	s_mov_b32 s3, -1
	v_mov_b64_e32 v[144:145], v[28:29]
	v_lshl_add_u64 v[146:147], v[28:29], 0, s[2:3]
	global_load_dwordx4 v[80:83], v[144:145], off offset:-16
	global_load_dwordx4 v[80:83], v[146:147], off
	v_lshl_add_u64 v[144:145], v[144:145], 0, vcc
	v_lshl_add_u64 v[146:147], v[146:147], 0, vcc
	global_load_dwordx4 v[80:83], v[144:145], off offset:-16
	global_load_dwordx4 v[80:83], v[146:147], off
	v_lshl_add_u64 v[144:145], v[144:145], 0, vcc
	v_lshl_add_u64 v[146:147], v[146:147], 0, vcc
	global_load_dwordx4 v[80:83], v[144:145], off offset:-16
	global_load_dwordx4 v[80:83], v[146:147], off
	v_lshl_add_u64 v[144:145], v[144:145], 0, vcc
	v_lshl_add_u64 v[146:147], v[146:147], 0, vcc
	global_load_dwordx4 v[80:83], v[144:145], off offset:-16
	global_load_dwordx4 v[80:83], v[146:147], off
	v_lshl_add_u64 v[144:145], v[144:145], 0, vcc
	v_lshl_add_u64 v[146:147], v[146:147], 0, vcc
	global_load_dwordx4 v[80:83], v[144:145], off offset:-16
	global_load_dwordx4 v[80:83], v[146:147], off
	v_lshl_add_u64 v[144:145], v[144:145], 0, vcc
	v_lshl_add_u64 v[146:147], v[146:147], 0, vcc
	global_load_dwordx4 v[80:83], v[144:145], off offset:-16
	global_load_dwordx4 v[80:83], v[146:147], off
	v_lshl_add_u64 v[144:145], v[144:145], 0, vcc
	v_lshl_add_u64 v[146:147], v[146:147], 0, vcc
	global_load_dwordx4 v[80:83], v[144:145], off offset:-16
	global_load_dwordx4 v[80:83], v[146:147], off
	v_lshl_add_u64 v[144:145], v[144:145], 0, vcc
	v_lshl_add_u64 v[146:147], v[146:147], 0, vcc
	global_load_dwordx4 v[80:83], v[144:145], off offset:-16
	global_load_dwordx4 v[80:83], v[146:147], off
	v_lshl_add_u64 v[144:145], v[144:145], 0, vcc
	v_lshl_add_u64 v[146:147], v[146:147], 0, vcc
	global_load_dwordx4 v[80:83], v[144:145], off offset:-16
	global_load_dwordx4 v[80:83], v[146:147], off
	v_lshl_add_u64 v[144:145], v[144:145], 0, vcc
	v_lshl_add_u64 v[146:147], v[146:147], 0, vcc
	global_load_dwordx4 v[80:83], v[144:145], off offset:-16
	global_load_dwordx4 v[80:83], v[146:147], off
	v_lshl_add_u64 v[144:145], v[144:145], 0, vcc
	v_lshl_add_u64 v[146:147], v[146:147], 0, vcc
	global_load_dwordx4 v[80:83], v[144:145], off offset:-16
	global_load_dwordx4 v[80:83], v[146:147], off
	v_lshl_add_u64 v[144:145], v[144:145], 0, vcc
	v_lshl_add_u64 v[146:147], v[146:147], 0, vcc
	global_load_dwordx4 v[80:83], v[144:145], off offset:-16
	global_load_dwordx4 v[80:83], v[146:147], off
	v_lshl_add_u64 v[144:145], v[144:145], 0, vcc
	v_lshl_add_u64 v[146:147], v[146:147], 0, vcc
	global_load_dwordx4 v[80:83], v[144:145], off offset:-16
	global_load_dwordx4 v[80:83], v[146:147], off
	v_lshl_add_u64 v[144:145], v[144:145], 0, vcc
	v_lshl_add_u64 v[146:147], v[146:147], 0, vcc
	global_load_dwordx4 v[80:83], v[144:145], off offset:-16
	global_load_dwordx4 v[80:83], v[146:147], off
	v_lshl_add_u64 v[144:145], v[144:145], 0, vcc
	v_lshl_add_u64 v[146:147], v[146:147], 0, vcc
	global_load_dwordx4 v[80:83], v[144:145], off offset:-16
	global_load_dwordx4 v[80:83], v[146:147], off
	v_lshl_add_u64 v[144:145], v[144:145], 0, vcc
	v_lshl_add_u64 v[146:147], v[146:147], 0, vcc
	global_load_dwordx4 v[80:83], v[144:145], off offset:-16
	global_load_dwordx4 v[80:83], v[146:147], off
	v_lshl_add_u64 v[144:145], v[144:145], 0, vcc
	v_lshl_add_u64 v[146:147], v[146:147], 0, vcc
	global_load_dwordx4 v[80:83], v[144:145], off offset:-16
	global_load_dwordx4 v[80:83], v[146:147], off
	v_lshl_add_u64 v[144:145], v[144:145], 0, vcc
	v_lshl_add_u64 v[146:147], v[146:147], 0, vcc
	global_load_dwordx4 v[80:83], v[144:145], off offset:-16
	global_load_dwordx4 v[80:83], v[146:147], off
	v_lshl_add_u64 v[144:145], v[144:145], 0, vcc
	v_lshl_add_u64 v[146:147], v[146:147], 0, vcc
	global_load_dwordx4 v[80:83], v[144:145], off offset:-16
	global_load_dwordx4 v[80:83], v[146:147], off
	v_lshl_add_u64 v[144:145], v[144:145], 0, vcc
	v_lshl_add_u64 v[146:147], v[146:147], 0, vcc
	global_load_dwordx4 v[80:83], v[144:145], off offset:-16
	global_load_dwordx4 v[80:83], v[146:147], off
	v_lshl_add_u64 v[144:145], v[144:145], 0, vcc
	v_lshl_add_u64 v[146:147], v[146:147], 0, vcc
	global_load_dwordx4 v[80:83], v[144:145], off offset:-16
	global_load_dwordx4 v[80:83], v[146:147], off
	v_lshl_add_u64 v[144:145], v[144:145], 0, vcc
	v_lshl_add_u64 v[146:147], v[146:147], 0, vcc
	global_load_dwordx4 v[80:83], v[144:145], off offset:-16
	global_load_dwordx4 v[80:83], v[146:147], off
	v_lshl_add_u64 v[144:145], v[144:145], 0, vcc
	v_lshl_add_u64 v[146:147], v[146:147], 0, vcc
	global_load_dwordx4 v[80:83], v[144:145], off offset:-16
	global_load_dwordx4 v[80:83], v[146:147], off
	v_lshl_add_u64 v[144:145], v[144:145], 0, vcc
	v_lshl_add_u64 v[146:147], v[146:147], 0, vcc
	global_load_dwordx4 v[80:83], v[144:145], off offset:-16
	global_load_dwordx4 v[80:83], v[146:147], off
	v_lshl_add_u64 v[144:145], v[144:145], 0, vcc
	v_lshl_add_u64 v[146:147], v[146:147], 0, vcc
	global_load_dwordx4 v[80:83], v[144:145], off offset:-16
	global_load_dwordx4 v[80:83], v[146:147], off
	v_lshl_add_u64 v[144:145], v[144:145], 0, vcc
	v_lshl_add_u64 v[146:147], v[146:147], 0, vcc
	global_load_dwordx4 v[80:83], v[144:145], off offset:-16
	global_load_dwordx4 v[80:83], v[146:147], off
	v_lshl_add_u64 v[144:145], v[144:145], 0, vcc
	v_lshl_add_u64 v[146:147], v[146:147], 0, vcc
	global_load_dwordx4 v[80:83], v[144:145], off offset:-16
	global_load_dwordx4 v[80:83], v[146:147], off
	v_lshl_add_u64 v[144:145], v[144:145], 0, vcc
	v_lshl_add_u64 v[146:147], v[146:147], 0, vcc
	global_load_dwordx4 v[80:83], v[144:145], off offset:-16
	global_load_dwordx4 v[80:83], v[146:147], off
	v_lshl_add_u64 v[144:145], v[144:145], 0, vcc
	v_lshl_add_u64 v[146:147], v[146:147], 0, vcc
	global_load_dwordx4 v[80:83], v[144:145], off offset:-16
	global_load_dwordx4 v[80:83], v[146:147], off
	v_lshl_add_u64 v[144:145], v[144:145], 0, vcc
	v_lshl_add_u64 v[146:147], v[146:147], 0, vcc
	global_load_dwordx4 v[80:83], v[144:145], off offset:-16
	global_load_dwordx4 v[80:83], v[146:147], off
	v_lshl_add_u64 v[144:145], v[144:145], 0, vcc
	v_lshl_add_u64 v[146:147], v[146:147], 0, vcc
	global_load_dwordx4 v[80:83], v[144:145], off offset:-16
	global_load_dwordx4 v[80:83], v[146:147], off
	v_lshl_add_u64 v[144:145], v[144:145], 0, vcc
	v_lshl_add_u64 v[146:147], v[146:147], 0, vcc
	global_load_dwordx4 v[80:83], v[144:145], off offset:-16
	global_load_dwordx4 v[80:83], v[146:147], off
